# MLA item prologue: first K/V tile loads issued at item-start barrier (on top of GQA tile-0 hoist)
# baseline (speedup 1.0000x reference)
.LBB0_115:
	s_and_b32 s20, s19, 7
	s_mul_i32 s12, s8, 0xc00
	s_mul_hi_i32 s11, s8, 0xc00
	s_add_u32 s12, s16, s12
	s_addc_u32 s11, s17, s11
	s_mul_i32 s13, s20, 0x180
	s_add_u32 s12, s12, s13
	s_addc_u32 s13, s11, 0
	v_lshl_add_u64 v[2:3], s[12:13], 0, v[166:167]
	v_lshl_add_u64 v[2:3], v[2:3], 0, v[0:1]
	s_barrier
	s_lshl_b32 s100, s20, 9
	s_add_u32 s100, s14, s100
	s_addc_u32 s101, s15, 0
	v_mov_b32_e32 v90, s10
	v_mov_b32_e32 v91, v1
	v_lshl_add_u64 v[66:67], v[90:91], 0, v[170:171]
	v_lshl_add_u64 v[70:71], v[174:175], 0, v[90:91]
	v_lshlrev_b64 v[86:87], 12, v[66:67]
	v_lshlrev_b64 v[70:71], 12, v[70:71]
	v_lshl_add_u64 v[74:75], v[90:91], 0, v[172:173]
	v_lshl_add_u64 v[66:67], s[100:101], 0, v[86:87]
	v_mov_b32_e32 v189, v1
	v_lshl_add_u64 v[70:71], s[100:101], 0, v[70:71]
	v_lshlrev_b64 v[88:89], 12, v[74:75]
	v_lshl_add_u64 v[78:79], v[66:67], 0, v[188:189]
	v_lshl_add_u64 v[82:83], v[70:71], 0, v[188:189]
	v_lshl_add_u64 v[74:75], v[176:177], 0, v[88:89]
	global_load_dwordx4 v[66:69], v[78:79], off
	global_load_dwordx4 v[70:73], v[82:83], off
	s_nop 0
	global_load_dwordx4 v[74:77], v[74:75], off
	s_nop 0
	global_load_dwordx4 v[78:81], v[78:79], off offset:256
	s_nop 0
	global_load_dwordx4 v[82:85], v[82:83], off offset:256
	s_nop 0
	s_nop 0
	s_nop 0
	s_nop 0
	s_nop 0
	s_nop 0
	s_nop 0
	s_nop 0
	s_nop 0
	s_nop 0
	s_nop 0
	s_nop 0
	s_nop 0
	s_nop 0
	s_nop 0
	s_nop 0
	s_nop 0
	s_nop 0
	s_nop 0
	s_nop 0
	s_nop 0
	s_nop 0
	s_nop 0
	s_nop 0
	s_nop 0
	s_nop 0
	s_nop 0
	s_nop 0
	s_nop 0
	s_nop 0
	s_nop 0
	s_nop 0
	s_nop 0
	s_nop 0
	s_nop 0
	s_nop 0
	global_load_dwordx4 v[134:137], v[2:3], off
	global_load_dwordx4 v[130:133], v[2:3], off offset:32
	global_load_dwordx4 v[126:129], v[2:3], off offset:64
	global_load_dwordx4 v[122:125], v[2:3], off offset:96
	global_load_dwordx4 v[118:121], v[2:3], off offset:128
	global_load_dwordx4 v[114:117], v[2:3], off offset:160
	global_load_dwordx4 v[110:113], v[2:3], off offset:192
	global_load_dwordx4 v[106:109], v[2:3], off offset:224
	global_load_dwordx4 v[102:105], v[2:3], off offset:256
	global_load_dwordx4 v[98:101], v[2:3], off offset:288
	global_load_dwordx4 v[138:141], v[2:3], off offset:320
	global_load_dwordx4 v[142:145], v[2:3], off offset:352
	s_cmp_gt_i32 s9, -1
	s_mov_b64 s[12:13], -1
	s_cbranch_scc1 .LBB0_117
	s_mov_b64 s[12:13], 0

.LBB0_119:
	s_mov_b32 s38, s10
	s_ashr_i32 s9, s8, 31
	s_lshl_b32 s11, s20, 9
	s_add_u32 s12, s14, s11
	s_addc_u32 s13, s15, 0
	s_ashr_i32 s11, s10, 31
	v_lshl_add_u64 v[2:3], s[10:11], 0, v[170:171]
	v_lshl_add_u64 v[6:7], v[174:175], 0, s[10:11]
	v_lshlrev_b64 v[22:23], 12, v[2:3]
	v_lshlrev_b64 v[6:7], 12, v[6:7]
	v_lshl_add_u64 v[10:11], s[10:11], 0, v[172:173]
	v_lshl_add_u64 v[2:3], s[12:13], 0, v[22:23]
	v_mov_b32_e32 v189, v1
	v_lshl_add_u64 v[6:7], s[12:13], 0, v[6:7]
	v_lshlrev_b64 v[24:25], 12, v[10:11]
	v_lshl_add_u64 v[14:15], v[2:3], 0, v[188:189]
	v_lshl_add_u64 v[18:19], v[6:7], 0, v[188:189]
	v_lshl_add_u64 v[10:11], v[176:177], 0, v[24:25]
	v_add_u32_e32 v26, 16, v198
	s_waitcnt vmcnt(0)
	s_and_b32 s22, s18, 7
	v_lshl_or_b32 v22, s22, 9, v22
	s_lshl_b32 s10, s21, 18
	v_lshl_add_u64 v[192:193], v[184:185], 0, v[24:25]
	v_lshl_add_u64 v[194:195], v[186:187], 0, v[22:23]
	s_add_u32 s21, s10, 0x40000
	s_mov_b32 s22, 0
	v_mov_b32_e32 v234, 0
	v_mov_b32_e32 v189, 0xf149f2ca
	s_mov_b64 s[10:11], 0
	s_waitcnt vmcnt(0)
	ds_write_b128 v26, v[78:81]
	v_add_u32_e32 v14, 16, v199
	s_waitcnt vmcnt(0)
	ds_write_b128 v14, v[82:85]
	v_add_u32_e32 v14, 16, v200
	ds_write_b128 v14, v[66:69] offset:32768
	ds_write_b128 v14, v[70:73] offset:45056
	v_add_u32_e32 v2, 16, v201
	v_mov_b32_e32 v16, v1
	v_mov_b32_e32 v17, v1
	ds_write_b128 v2, v[74:77] offset:32768
	v_mov_b32_e32 v2, v1
	v_mov_b32_e32 v3, v1
	v_mov_b32_e32 v4, v1
	v_mov_b32_e32 v5, v1
	v_mov_b32_e32 v6, v1
	v_mov_b32_e32 v7, v1
	v_mov_b32_e32 v8, v1
	v_mov_b32_e32 v9, v1
	v_mov_b32_e32 v10, v1
	v_mov_b32_e32 v11, v1
	v_mov_b32_e32 v12, v1
	v_mov_b32_e32 v13, v1
	v_mov_b32_e32 v14, v1
	v_mov_b32_e32 v15, v1
	v_mov_b64_e32 v[32:33], v[16:17]
	v_mov_b64_e32 v[48:49], v[16:17]
	v_mov_b64_e32 v[64:65], v[16:17]
	v_mov_b64_e32 v[30:31], v[14:15]
	v_mov_b64_e32 v[28:29], v[12:13]
	v_mov_b64_e32 v[26:27], v[10:11]
	v_mov_b64_e32 v[24:25], v[8:9]
	v_mov_b64_e32 v[22:23], v[6:7]
	v_mov_b64_e32 v[20:21], v[4:5]
	v_mov_b64_e32 v[18:19], v[2:3]
	v_mov_b64_e32 v[46:47], v[14:15]
	v_mov_b64_e32 v[44:45], v[12:13]
	v_mov_b64_e32 v[42:43], v[10:11]
	v_mov_b64_e32 v[40:41], v[8:9]
	v_mov_b64_e32 v[38:39], v[6:7]
	v_mov_b64_e32 v[36:37], v[4:5]
	v_mov_b64_e32 v[34:35], v[2:3]
	v_mov_b64_e32 v[62:63], v[14:15]
	v_mov_b64_e32 v[60:61], v[12:13]
	v_mov_b64_e32 v[58:59], v[10:11]
	v_mov_b64_e32 v[56:57], v[8:9]
	v_mov_b64_e32 v[54:55], v[6:7]
	v_mov_b64_e32 v[52:53], v[4:5]
	v_mov_b64_e32 v[50:51], v[2:3]
	s_waitcnt lgkmcnt(0)
	s_barrier
	s_lshl_b32 s12, s20, 9
	s_add_i32 s12, s12, 0x8400000
	v_and_b32_e32 v66, 63, v178
	v_lshrrev_b32_e32 v67, 6, v178
	v_mul_u32_u24_e32 v68, 0xc0, v67
	v_add_u32_e32 v68, v68, v66
	v_mul_u32_u24_e32 v70, 0xaab, v68
	v_lshrrev_b32_e32 v70, 16, v70
	v_mul_u32_u24_e32 v71, 24, v70
	v_sub_u32_e32 v71, v68, v71
	v_and_b32_e32 v72, 15, v70
	v_xor_b32_e32 v72, v71, v72
	v_lshlrev_b32_e32 v72, 4, v72
	v_add_u32_e32 v72, s12, v72
	v_add_u32_e32 v73, -16, v71
	v_and_b32_e32 v74, 7, v70
	v_xor_b32_e32 v73, v73, v74
	v_lshlrev_b32_e32 v73, 4, v73
	v_add_u32_e32 v73, 0x600, v73
	v_cmp_gt_u32_e32 vcc, 16, v71
	s_nop 1
	v_cndmask_b32_e32 v72, v73, v72, vcc
	v_lshl_add_u32 v247, v70, 12, v72
	v_add_u32_e32 v68, 64, v68
	v_mul_u32_u24_e32 v70, 0xaab, v68
	v_lshrrev_b32_e32 v70, 16, v70
	v_mul_u32_u24_e32 v71, 24, v70
	v_sub_u32_e32 v71, v68, v71
	v_and_b32_e32 v72, 15, v70
	v_xor_b32_e32 v72, v71, v72
	v_lshlrev_b32_e32 v72, 4, v72
	v_add_u32_e32 v72, s12, v72
	v_add_u32_e32 v73, -16, v71
	v_and_b32_e32 v74, 7, v70
	v_xor_b32_e32 v73, v73, v74
	v_lshlrev_b32_e32 v73, 4, v73
	v_add_u32_e32 v73, 0x600, v73
	v_cmp_gt_u32_e32 vcc, 16, v71
	s_nop 1
	v_cndmask_b32_e32 v72, v73, v72, vcc
	v_lshl_add_u32 v248, v70, 12, v72
	v_add_u32_e32 v68, 64, v68
	v_mul_u32_u24_e32 v70, 0xaab, v68
	v_lshrrev_b32_e32 v70, 16, v70
	v_mul_u32_u24_e32 v71, 24, v70
	v_sub_u32_e32 v71, v68, v71
	v_and_b32_e32 v72, 15, v70
	v_xor_b32_e32 v72, v71, v72
	v_lshlrev_b32_e32 v72, 4, v72
	v_add_u32_e32 v72, s12, v72
	v_add_u32_e32 v73, -16, v71
	v_and_b32_e32 v74, 7, v70
	v_xor_b32_e32 v73, v73, v74
	v_lshlrev_b32_e32 v73, 4, v73
	v_add_u32_e32 v73, 0x600, v73
	v_cmp_gt_u32_e32 vcc, 16, v71
	s_nop 1
	v_cndmask_b32_e32 v72, v73, v72, vcc
	v_lshl_add_u32 v249, v70, 12, v72
	v_and_b32_e32 v70, 31, v66
	v_lshrrev_b32_e32 v70, 2, v70
	v_lshl_add_u32 v70, v67, 3, v70
	v_lshrrev_b32_e32 v71, 5, v66
	v_lshlrev_b32_e32 v71, 6, v71
	v_and_b32_e32 v72, 3, v66
	v_lshlrev_b32_e32 v72, 4, v72
	v_add3_u32 v71, v71, v72, s12
	v_add_u32_e32 v71, 0x100, v71
	v_lshl_add_u32 v250, v70, 12, v71
	v_add_u32_e32 v251, 0x80, v250
	s_add_i32 s24, s38, 64
	s_lshl_b32 s24, s24, 12
	s_add_u32 s24, s24, 0x4600000
	s_add_u32 s24, s98, s24
	s_addc_u32 s25, s99, 0
	v_readlane_b32 s26, v254, 10
	s_nop 3
	s_lshr_b32 s36, s26, 6
	s_lshl_b32 s26, s26, 5
	s_add_i32 s26, s26, 16
	s_mul_i32 s36, s36, 0xc00
	s_add_i32 s36, s36, 0x8010
	s_movk_i32 s12, 0x2000
	v_add3_u32 v146, v203, v220, s12
	v_add3_u32 v147, v203, v221, s12
	v_add3_u32 v163, v203, v222, s12
	v_add3_u32 v164, v203, v223, s12
	v_add3_u32 v165, v203, v224, s12
	v_add3_u32 v156, v203, v225, s12
	v_add3_u32 v157, v203, v226, s12
	v_add3_u32 v158, v203, v227, s12
	v_add3_u32 v159, v203, v228, s12
	v_add3_u32 v160, v203, v229, s12
	v_add3_u32 v161, v203, v230, s12
	v_add3_u32 v162, v203, v231, s12
	s_mov_b32 s30, 0x13572468
	s_mov_b32 s30, 0x13572468
	s_mov_b32 s30, 0x13572468
	s_mov_b32 s30, 0x13572468
	s_mov_b32 s30, 0x13572468
	s_mov_b32 s30, 0x13572468
	s_mov_b32 s30, 0x13572468
	s_add_i32 m0, s36, 0x6000
	s_nop 0
	global_load_lds_dwordx4 v247, s[24:25]
	s_add_i32 m0, s36, 0x6400
	s_nop 0
	global_load_lds_dwordx4 v248, s[24:25]
	s_add_i32 m0, s36, 0x6800
	s_nop 0
	global_load_lds_dwordx4 v249, s[24:25]
	s_add_u32 s24, s24, 0x40000
	s_addc_u32 s25, s25, 0
	s_branch .Lmu_b120
